# v81 + SwiGLU epilogue: log2e folded into per-row rstd, exp2 takes -g via neg modifier (96 v_mul removed), (1+e)*log2e^2 via one v_fma; f32 throughout
# baseline (speedup 1.0000x reference)
; __device__ __forceinline__ unsigned cvt_pk_bf16(float lo, float hi) { unsigned r; asm volatile("v_cvt_pk_bf16_f32 %0, %1, %2" : "=v"(r) : "v"(lo), "v"(hi)); return r; }
; __device__ __forceinline__ float silu_mul(float g, float u) { const float e = __builtin_amdgcn_exp2f(g * -1.4426950408889634f); return g * u * __builtin_amdgcn_rcpf(1.0f + e); }
;     __device__ __forceinline__ void operator()(const f32x4 (&acc)[2][2][4][2], const Unit& u, int wr, int wc, int fr, int fq, const PG8_LAS float* rc, bool cached) const {
;     ...
;             for (int m = 0; m < 4; ++m) { const int row = row0 + ai * HALF + m * 16; const float rs = rsv[ai * 4 + m];
;                 const f32x4 g0 = acc[ai][0][m][0] * rs, g1 = acc[ai][0][m][1] * rs, u0 = acc[ai][1][m][0] * rs, u1 = acc[ai][1][m][1] * rs;
;                 u32x4 w; w.x = cvt_pk_bf16(silu_mul(g0[0], u0[0]), silu_mul(g0[1], u0[1])); w.y = cvt_pk_bf16(silu_mul(g0[2], u0[2]), silu_mul(g0[3], u0[3]));
;                 w.z = cvt_pk_bf16(silu_mul(g1[0], u1[0]), silu_mul(g1[1], u1[1])); w.w = cvt_pk_bf16(silu_mul(g1[2], u1[2]), silu_mul(g1[3], u1[3]));
;                 *(u32x4*)(H + (size_t)row * 5632 + col0) = w; }
.LBB0_170:
	s_waitcnt lgkmcnt(0)
	v_mul_f32_e32 v0, 0x3fb8aa3b, v0
	v_mul_f32_e32 v1, 0x3fb8aa3b, v1
	v_mul_f32_e32 v2, 0x3fb8aa3b, v2
	v_mul_f32_e32 v3, 0x3fb8aa3b, v3
	v_mul_f32_e32 v4, 0x3fb8aa3b, v4
	v_mul_f32_e32 v5, 0x3fb8aa3b, v5
	v_mul_f32_e32 v6, 0x3fb8aa3b, v6
	v_mul_f32_e32 v7, 0x3fb8aa3b, v7
	v_mov_b32_e32 v251, 0x40053526
	v_pk_mul_f32 v[132:133], v[132:133], v[0:1] op_sel_hi:[1,0]
	v_pk_mul_f32 v[124:125], v[124:125], v[0:1] op_sel_hi:[1,0]
	v_exp_f32_e64 v140, -v132
	v_mul_f32_e32 v124, v132, v124
	v_mul_f32_e32 v125, v133, v125
	v_pk_mul_f32 v[134:135], v[134:135], v[0:1] op_sel_hi:[1,0]
	v_fma_f32 v132, v140, v251, v251
	v_rcp_f32_e32 v132, v132
	v_pk_mul_f32 v[126:127], v[126:127], v[0:1] op_sel_hi:[1,0]
	v_pk_mul_f32 v[128:129], v[128:129], v[0:1] op_sel_hi:[1,0]
	v_mul_f32_e32 v126, v134, v126
	v_mul_f32_e32 v124, v124, v132
	v_exp_f32_e64 v132, -v133
	v_mul_f32_e32 v127, v135, v127
	v_pk_mul_f32 v[120:121], v[120:121], v[0:1] op_sel_hi:[1,0]
	v_pk_mul_f32 v[130:131], v[130:131], v[0:1] op_sel_hi:[1,0]
	v_fma_f32 v132, v132, v251, v251
	v_rcp_f32_e32 v132, v132
	v_mul_f32_e32 v120, v128, v120
	v_mul_f32_e32 v121, v129, v121
	v_pk_mul_f32 v[122:123], v[122:123], v[0:1] op_sel_hi:[1,0]
	v_mul_f32_e32 v125, v125, v132
	v_cvt_pk_bf16_f32 v124, v124, v125
	v_exp_f32_e64 v125, -v134
	v_lshl_or_b32 v138, s49, 7, v207
	v_add_u32_e32 v138, v138, v209
	v_ashrrev_i32_e32 v139, 31, v138
	v_fma_f32 v125, v125, v251, v251
	v_rcp_f32_e32 v125, v125
	v_pk_mul_f32 v[116:117], v[116:117], v[0:1] op_sel:[0,1]
	v_pk_mul_f32 v[118:119], v[118:119], v[0:1] op_sel:[0,1]
	v_pk_mul_f32 v[114:115], v[114:115], v[0:1] op_sel:[0,1]
	v_mul_f32_e32 v125, v126, v125
	v_exp_f32_e64 v126, -v135
	v_pk_mul_f32 v[112:113], v[112:113], v[0:1] op_sel:[0,1]
	v_pk_mul_f32 v[110:111], v[110:111], v[0:1] op_sel:[0,1]
	v_pk_mul_f32 v[108:109], v[108:109], v[0:1] op_sel:[0,1]
	v_fma_f32 v126, v126, v251, v251
	v_rcp_f32_e32 v126, v126
	v_pk_mul_f32 v[100:101], v[100:101], v[2:3] op_sel_hi:[1,0]
	v_pk_mul_f32 v[98:99], v[98:99], v[2:3] op_sel_hi:[1,0]
	v_pk_mul_f32 v[96:97], v[96:97], v[2:3] op_sel_hi:[1,0]
	v_mul_f32_e32 v126, v127, v126
	v_cvt_pk_bf16_f32 v125, v125, v126
	v_exp_f32_e64 v126, -v128
	v_pk_mul_f32 v[94:95], v[94:95], v[2:3] op_sel_hi:[1,0]
	v_pk_mul_f32 v[92:93], v[92:93], v[2:3] op_sel_hi:[1,0]
	v_pk_mul_f32 v[66:67], v[66:67], v[4:5] op_sel_hi:[1,0]
	v_fma_f32 v126, v126, v251, v251
	v_rcp_f32_e32 v126, v126
	v_pk_mul_f32 v[64:65], v[64:65], v[4:5] op_sel_hi:[1,0]
	v_pk_mul_f32 v[62:63], v[62:63], v[4:5] op_sel_hi:[1,0]
	v_pk_mul_f32 v[60:61], v[60:61], v[4:5] op_sel_hi:[1,0]
	v_mul_f32_e32 v120, v120, v126
	v_exp_f32_e64 v126, -v129
	v_pk_mul_f32 v[58:59], v[58:59], v[4:5] op_sel_hi:[1,0]
	v_pk_mul_f32 v[56:57], v[56:57], v[4:5] op_sel_hi:[1,0]
	v_pk_mul_f32 v[32:33], v[32:33], v[6:7] op_sel_hi:[1,0]
	v_fma_f32 v126, v126, v251, v251
	v_rcp_f32_e32 v126, v126
	v_pk_mul_f32 v[30:31], v[30:31], v[6:7] op_sel_hi:[1,0]
	v_pk_mul_f32 v[28:29], v[28:29], v[6:7] op_sel_hi:[1,0]
	v_pk_mul_f32 v[26:27], v[26:27], v[6:7] op_sel_hi:[1,0]
	v_mul_f32_e32 v121, v121, v126
	v_cvt_pk_bf16_f32 v126, v120, v121
	v_exp_f32_e64 v120, -v130
	v_mul_f32_e32 v121, v130, v122
	v_mul_f32_e32 v122, v131, v123
	v_pk_mul_f32 v[24:25], v[24:25], v[6:7] op_sel_hi:[1,0]
	v_fma_f32 v120, v120, v251, v251
	v_rcp_f32_e32 v120, v120
	s_andn2_b64 vcc, exec, s[4:5]
	v_mul_f32_e32 v120, v121, v120
	v_exp_f32_e64 v121, -v131
	s_nop 0
	v_fma_f32 v121, v121, v251, v251
	v_rcp_f32_e32 v121, v121
	s_nop 0
	v_mul_f32_e32 v121, v122, v121
	v_cvt_pk_bf16_f32 v127, v120, v121
	v_mov_b64_e32 v[120:121], s[16:17]
	v_mad_u64_u32 v[128:129], s[6:7], v200, s57, v[120:121]
	v_mov_b32_e32 v122, v129
	v_mad_u64_u32 v[122:123], s[6:7], v201, s57, v[122:123]
	v_mov_b32_e32 v129, v122
	v_lshlrev_b64 v[122:123], 1, v[138:139]
	v_lshl_add_u64 v[128:129], v[128:129], 0, v[122:123]
	global_store_dwordx4 v[128:129], v[124:127], off
	s_nop 1
	v_pk_mul_f32 v[124:125], v[106:107], v[0:1] op_sel:[0,1]
	v_pk_mul_f32 v[0:1], v[104:105], v[0:1] op_sel:[0,1]
	v_exp_f32_e64 v104, -v116
	v_mul_f32_e32 v105, v116, v108
	v_mul_f32_e32 v106, v117, v109
	v_mul_f32_e32 v107, v119, v111
	v_fma_f32 v104, v104, v251, v251
	v_rcp_f32_e32 v104, v104
	v_mul_f32_e32 v0, v112, v0
	v_mul_f32_e32 v1, v113, v1
	v_mul_f32_e32 v104, v105, v104
	v_exp_f32_e64 v105, -v117
	s_nop 0
	v_fma_f32 v105, v105, v251, v251
	v_rcp_f32_e32 v105, v105
	s_nop 0
	v_mul_f32_e32 v105, v106, v105
	v_cvt_pk_bf16_f32 v104, v104, v105
	v_exp_f32_e64 v105, -v118
	v_mul_f32_e32 v106, v118, v110
	v_fma_f32 v105, v105, v251, v251
	v_rcp_f32_e32 v105, v105
	s_nop 0
	v_mul_f32_e32 v105, v106, v105
	v_exp_f32_e64 v106, -v119
	s_nop 0
	v_fma_f32 v106, v106, v251, v251
	v_rcp_f32_e32 v106, v106
	s_nop 0
	v_mul_f32_e32 v106, v107, v106
	v_cvt_pk_bf16_f32 v105, v105, v106
	v_exp_f32_e64 v106, -v112
	v_mul_f32_e32 v107, v115, v125
	v_fma_f32 v106, v106, v251, v251
	v_rcp_f32_e32 v106, v106
	s_nop 0
	v_mul_f32_e32 v0, v0, v106
	v_exp_f32_e64 v106, -v113
	s_nop 0
	v_fma_f32 v106, v106, v251, v251
	v_rcp_f32_e32 v106, v106
	s_nop 0
	v_mul_f32_e32 v1, v1, v106
	v_cvt_pk_bf16_f32 v106, v0, v1
	v_exp_f32_e64 v0, -v114
	v_mul_f32_e32 v1, v114, v124
	v_fma_f32 v0, v0, v251, v251
	v_rcp_f32_e32 v0, v0
	s_nop 0
	v_mul_f32_e32 v0, v1, v0
	v_exp_f32_e64 v1, -v115
	s_nop 0
	v_fma_f32 v1, v1, v251, v251
	v_rcp_f32_e32 v1, v1
	s_nop 0
	v_mul_f32_e32 v1, v107, v1
	v_cvt_pk_bf16_f32 v107, v0, v1
	v_mad_u64_u32 v[0:1], s[6:7], v198, s57, v[120:121]
	v_mov_b32_e32 v108, v1
	v_mad_u64_u32 v[108:109], s[6:7], v199, s57, v[108:109]
	v_mov_b32_e32 v1, v108
	v_lshl_add_u64 v[0:1], v[0:1], 0, v[122:123]
; __device__ __forceinline__ unsigned cvt_pk_bf16(float lo, float hi) { unsigned r; asm volatile("v_cvt_pk_bf16_f32 %0, %1, %2" : "=v"(r) : "v"(lo), "v"(hi)); return r; }
; __device__ __forceinline__ float silu_mul(float g, float u) { const float e = __builtin_amdgcn_exp2f(g * -1.4426950408889634f); return g * u * __builtin_amdgcn_rcpf(1.0f + e); }
;     __device__ __forceinline__ void operator()(const f32x4 (&acc)[2][2][4][2], const Unit& u, int wr, int wc, int fr, int fq, const PG8_LAS float* rc, bool cached) const {
;     ...
;             for (int m = 0; m < 4; ++m) { const int row = row0 + ai * HALF + m * 16; const float rs = rsv[ai * 4 + m];
;                 const f32x4 g0 = acc[ai][0][m][0] * rs, g1 = acc[ai][0][m][1] * rs, u0 = acc[ai][1][m][0] * rs, u1 = acc[ai][1][m][1] * rs;
;                 u32x4 w; w.x = cvt_pk_bf16(silu_mul(g0[0], u0[0]), silu_mul(g0[1], u0[1])); w.y = cvt_pk_bf16(silu_mul(g0[2], u0[2]), silu_mul(g0[3], u0[3]));
;                 w.z = cvt_pk_bf16(silu_mul(g1[0], u1[0]), silu_mul(g1[1], u1[1])); w.w = cvt_pk_bf16(silu_mul(g1[2], u1[2]), silu_mul(g1[3], u1[3]));
;                 *(u32x4*)(H + (size_t)row * 5632 + col0) = w; }
	global_store_dwordx4 v[0:1], v[104:107], off
	v_pk_mul_f32 v[0:1], v[102:103], v[2:3] op_sel_hi:[1,0]
	v_pk_mul_f32 v[102:103], v[90:91], v[2:3] op_sel_hi:[1,0]
	v_pk_mul_f32 v[90:91], v[88:89], v[2:3] op_sel_hi:[1,0]
	v_exp_f32_e64 v2, -v100
	v_mul_f32_e32 v88, v100, v92
	v_mul_f32_e32 v89, v101, v93
	v_fma_f32 v2, v2, v251, v251
	v_rcp_f32_e32 v2, v2
	s_nop 0
	v_mul_f32_e32 v2, v88, v2
	v_exp_f32_e64 v88, -v101
	s_nop 0
	v_fma_f32 v88, v88, v251, v251
	v_rcp_f32_e32 v88, v88
	s_nop 0
	v_mul_f32_e32 v88, v89, v88
	v_cvt_pk_bf16_f32 v88, v2, v88
	v_exp_f32_e64 v2, -v0
	v_mul_f32_e32 v0, v0, v94
	v_fma_f32 v2, v2, v251, v251
	v_rcp_f32_e32 v2, v2
	s_nop 0
	v_mul_f32_e32 v0, v0, v2
	v_exp_f32_e64 v2, -v1
	v_mul_f32_e32 v1, v1, v95
	v_fma_f32 v2, v2, v251, v251
	v_rcp_f32_e32 v2, v2
	s_nop 0
	v_mul_f32_e32 v1, v1, v2
	v_cvt_pk_bf16_f32 v89, v0, v1
	v_exp_f32_e64 v0, -v96
	v_mul_f32_e32 v1, v96, v90
	v_mul_f32_e32 v2, v97, v91
	v_fma_f32 v0, v0, v251, v251
	v_rcp_f32_e32 v0, v0
	s_nop 0
	v_mul_f32_e32 v0, v1, v0
	v_exp_f32_e64 v1, -v97
	s_nop 0
	v_fma_f32 v1, v1, v251, v251
	v_rcp_f32_e32 v1, v1
	s_nop 0
	v_mul_f32_e32 v1, v2, v1
	v_cvt_pk_bf16_f32 v90, v0, v1
	v_exp_f32_e64 v0, -v98
	v_mul_f32_e32 v1, v98, v102
	v_mul_f32_e32 v2, v99, v103
	v_fma_f32 v0, v0, v251, v251
	v_rcp_f32_e32 v0, v0
	s_nop 0
	v_mul_f32_e32 v0, v1, v0
	v_exp_f32_e64 v1, -v99
	s_nop 0
	v_fma_f32 v1, v1, v251, v251
	v_rcp_f32_e32 v1, v1
	s_nop 0
	v_mul_f32_e32 v1, v2, v1
	v_cvt_pk_bf16_f32 v91, v0, v1
	v_mad_u64_u32 v[0:1], s[6:7], v196, s57, v[120:121]
	v_mov_b32_e32 v2, v1
	v_mad_u64_u32 v[92:93], s[6:7], v197, s57, v[2:3]
	v_mov_b32_e32 v1, v92
	v_lshl_add_u64 v[0:1], v[0:1], 0, v[122:123]
	global_store_dwordx4 v[0:1], v[88:91], off
	v_mov_b32_e32 v0, v3
	v_pk_mul_f32 v[84:85], v[84:85], v[0:1] op_sel_hi:[1,0]
	v_pk_mul_f32 v[2:3], v[86:87], v[0:1] op_sel_hi:[1,0]
	v_pk_mul_f32 v[82:83], v[82:83], v[0:1] op_sel_hi:[1,0]
	v_pk_mul_f32 v[80:81], v[80:81], v[0:1] op_sel_hi:[1,0]
	v_pk_mul_f32 v[78:79], v[78:79], v[0:1] op_sel_hi:[1,0]
	v_pk_mul_f32 v[76:77], v[76:77], v[0:1] op_sel_hi:[1,0]
	v_pk_mul_f32 v[74:75], v[74:75], v[0:1] op_sel_hi:[1,0]
	v_pk_mul_f32 v[72:73], v[72:73], v[0:1] op_sel_hi:[1,0]
	v_exp_f32_e64 v0, -v84
	v_mul_f32_e32 v1, v84, v76
	v_mul_f32_e32 v76, v85, v77
	v_fma_f32 v0, v0, v251, v251
	v_rcp_f32_e32 v0, v0
	s_nop 0
	v_mul_f32_e32 v0, v1, v0
	v_exp_f32_e64 v1, -v85
	s_nop 0
	v_fma_f32 v1, v1, v251, v251
	v_rcp_f32_e32 v1, v1
	s_nop 0
	v_mul_f32_e32 v1, v76, v1
	v_cvt_pk_bf16_f32 v0, v0, v1
	v_exp_f32_e64 v1, -v2
	v_mul_f32_e32 v2, v2, v78
	v_fma_f32 v1, v1, v251, v251
	v_rcp_f32_e32 v1, v1
	s_nop 0
	v_mul_f32_e32 v1, v2, v1
	v_exp_f32_e64 v2, -v3
	v_mul_f32_e32 v3, v3, v79
	v_fma_f32 v2, v2, v251, v251
	v_rcp_f32_e32 v2, v2
	s_nop 0
	v_mul_f32_e32 v2, v3, v2
	v_cvt_pk_bf16_f32 v1, v1, v2
	v_exp_f32_e64 v2, -v80
	v_mul_f32_e32 v3, v80, v72
	v_mul_f32_e32 v72, v81, v73
	v_mul_f32_e32 v73, v83, v75
	v_fma_f32 v2, v2, v251, v251
	v_rcp_f32_e32 v2, v2
	s_nop 0
	v_mul_f32_e32 v2, v3, v2
	v_exp_f32_e64 v3, -v81
	s_nop 0
	v_fma_f32 v3, v3, v251, v251
	v_rcp_f32_e32 v3, v3
	s_nop 0
	v_mul_f32_e32 v3, v72, v3
	v_cvt_pk_bf16_f32 v2, v2, v3
	v_exp_f32_e64 v3, -v82
	v_mul_f32_e32 v72, v82, v74
	v_fma_f32 v3, v3, v251, v251
	v_rcp_f32_e32 v3, v3
	s_nop 0
	v_mul_f32_e32 v3, v72, v3
	v_exp_f32_e64 v72, -v83
	s_nop 0
	v_fma_f32 v72, v72, v251, v251
	v_rcp_f32_e32 v72, v72
	s_nop 0
	v_mul_f32_e32 v72, v73, v72
	v_cvt_pk_bf16_f32 v3, v3, v72
	v_mad_u64_u32 v[72:73], s[6:7], v194, s57, v[120:121]
	v_mov_b32_e32 v74, v73
	v_mad_u64_u32 v[74:75], s[6:7], v195, s57, v[74:75]
	v_mov_b32_e32 v73, v74
	v_lshl_add_u64 v[72:73], v[72:73], 0, v[122:123]
	global_store_dwordx4 v[72:73], v[0:3], off
	s_nop 1
	v_pk_mul_f32 v[0:1], v[68:69], v[4:5] op_sel_hi:[1,0]
	v_pk_mul_f32 v[2:3], v[70:71], v[4:5] op_sel_hi:[1,0]
	v_exp_f32_e64 v4, -v0
	v_mul_f32_e32 v0, v0, v60
	v_fma_f32 v4, v4, v251, v251
	v_rcp_f32_e32 v4, v4
	s_nop 0
	v_mul_f32_e32 v0, v0, v4
	v_exp_f32_e64 v4, -v1
	v_mul_f32_e32 v1, v1, v61
	v_fma_f32 v4, v4, v251, v251
	v_rcp_f32_e32 v4, v4
	s_nop 0
	v_mul_f32_e32 v1, v1, v4
	v_cvt_pk_bf16_f32 v0, v0, v1
	v_exp_f32_e64 v1, -v2
	v_mul_f32_e32 v2, v2, v62
	v_mul_f32_e32 v4, v65, v57
	v_fma_f32 v1, v1, v251, v251
	v_rcp_f32_e32 v1, v1
	s_nop 0
	v_mul_f32_e32 v1, v2, v1
	v_exp_f32_e64 v2, -v3
	v_mul_f32_e32 v3, v3, v63
	v_fma_f32 v2, v2, v251, v251
	v_rcp_f32_e32 v2, v2
	s_nop 0
	v_mul_f32_e32 v2, v3, v2
	v_cvt_pk_bf16_f32 v1, v1, v2
	v_exp_f32_e64 v2, -v64
	v_mul_f32_e32 v3, v64, v56
	v_mul_f32_e32 v56, v67, v59
	v_fma_f32 v2, v2, v251, v251
	v_rcp_f32_e32 v2, v2
	s_nop 0
	v_mul_f32_e32 v2, v3, v2
	v_exp_f32_e64 v3, -v65
	s_nop 0
	v_fma_f32 v3, v3, v251, v251
	v_rcp_f32_e32 v3, v3
	s_nop 0
	v_mul_f32_e32 v3, v4, v3
	v_cvt_pk_bf16_f32 v2, v2, v3
	v_exp_f32_e64 v3, -v66
	v_mul_f32_e32 v4, v66, v58
	v_fma_f32 v3, v3, v251, v251
	v_rcp_f32_e32 v3, v3
	s_nop 0
	v_mul_f32_e32 v3, v4, v3
	v_exp_f32_e64 v4, -v67
	s_nop 0
	v_fma_f32 v4, v4, v251, v251
	v_rcp_f32_e32 v4, v4
	s_nop 0
	v_mul_f32_e32 v4, v56, v4
	v_mad_u64_u32 v[56:57], s[6:7], v136, s57, v[120:121]
	v_cvt_pk_bf16_f32 v3, v3, v4
	v_mov_b32_e32 v4, v57
	v_mad_u64_u32 v[58:59], s[6:7], v137, s57, v[4:5]
	v_mov_b32_e32 v57, v58
	v_lshl_add_u64 v[56:57], v[56:57], 0, v[122:123]
	global_store_dwordx4 v[56:57], v[0:3], off
	v_add_u32_e32 v56, 16, v192
	s_nop 0
	v_mov_b32_e32 v0, v5
; __device__ __forceinline__ unsigned cvt_pk_bf16(float lo, float hi) { unsigned r; asm volatile("v_cvt_pk_bf16_f32 %0, %1, %2" : "=v"(r) : "v"(lo), "v"(hi)); return r; }
; __device__ __forceinline__ float silu_mul(float g, float u) { const float e = __builtin_amdgcn_exp2f(g * -1.4426950408889634f); return g * u * __builtin_amdgcn_rcpf(1.0f + e); }
;     __device__ __forceinline__ void operator()(const f32x4 (&acc)[2][2][4][2], const Unit& u, int wr, int wc, int fr, int fq, const PG8_LAS float* rc, bool cached) const {
;     ...
;             for (int m = 0; m < 4; ++m) { const int row = row0 + ai * HALF + m * 16; const float rs = rsv[ai * 4 + m];
;                 const f32x4 g0 = acc[ai][0][m][0] * rs, g1 = acc[ai][0][m][1] * rs, u0 = acc[ai][1][m][0] * rs, u1 = acc[ai][1][m][1] * rs;
;                 u32x4 w; w.x = cvt_pk_bf16(silu_mul(g0[0], u0[0]), silu_mul(g0[1], u0[1])); w.y = cvt_pk_bf16(silu_mul(g0[2], u0[2]), silu_mul(g0[3], u0[3]));
;                 w.z = cvt_pk_bf16(silu_mul(g1[0], u1[0]), silu_mul(g1[1], u1[1])); w.w = cvt_pk_bf16(silu_mul(g1[2], u1[2]), silu_mul(g1[3], u1[3]));
;                 *(u32x4*)(H + (size_t)row * 5632 + col0) = w; }
	v_pk_mul_f32 v[4:5], v[52:53], v[0:1] op_sel_hi:[1,0]
	v_pk_mul_f32 v[2:3], v[54:55], v[0:1] op_sel_hi:[1,0]
	v_pk_mul_f32 v[50:51], v[50:51], v[0:1] op_sel_hi:[1,0]
	v_pk_mul_f32 v[48:49], v[48:49], v[0:1] op_sel_hi:[1,0]
	v_pk_mul_f32 v[46:47], v[46:47], v[0:1] op_sel_hi:[1,0]
	v_pk_mul_f32 v[44:45], v[44:45], v[0:1] op_sel_hi:[1,0]
	v_pk_mul_f32 v[42:43], v[42:43], v[0:1] op_sel_hi:[1,0]
	v_pk_mul_f32 v[40:41], v[40:41], v[0:1] op_sel_hi:[1,0]
	v_exp_f32_e64 v0, -v4
	v_mul_f32_e32 v1, v4, v44
	v_mul_f32_e32 v4, v5, v45
	v_fma_f32 v0, v0, v251, v251
	v_rcp_f32_e32 v0, v0
	s_nop 0
	v_mul_f32_e32 v0, v1, v0
	v_exp_f32_e64 v1, -v5
	v_mul_f32_e32 v5, v51, v43
	v_fma_f32 v1, v1, v251, v251
	v_rcp_f32_e32 v1, v1
	s_nop 0
	v_mul_f32_e32 v1, v4, v1
	v_cvt_pk_bf16_f32 v0, v0, v1
	v_exp_f32_e64 v1, -v2
	v_mul_f32_e32 v2, v2, v46
	v_mul_f32_e32 v4, v49, v41
	v_fma_f32 v1, v1, v251, v251
	v_rcp_f32_e32 v1, v1
	s_nop 0
	v_mul_f32_e32 v1, v2, v1
	v_exp_f32_e64 v2, -v3
	v_mul_f32_e32 v3, v3, v47
	v_fma_f32 v2, v2, v251, v251
	v_rcp_f32_e32 v2, v2
	s_nop 0
	v_mul_f32_e32 v2, v3, v2
	v_cvt_pk_bf16_f32 v1, v1, v2
	v_exp_f32_e64 v2, -v48
	v_mul_f32_e32 v3, v48, v40
	v_add_u32_e32 v40, 32, v192
	v_fma_f32 v2, v2, v251, v251
	v_rcp_f32_e32 v2, v2
	s_nop 0
	v_mul_f32_e32 v2, v3, v2
	v_exp_f32_e64 v3, -v49
	s_nop 0
	v_fma_f32 v3, v3, v251, v251
	v_rcp_f32_e32 v3, v3
	s_nop 0
	v_mul_f32_e32 v3, v4, v3
	v_cvt_pk_bf16_f32 v2, v2, v3
	v_exp_f32_e64 v3, -v50
	v_mul_f32_e32 v4, v50, v42
	v_fma_f32 v3, v3, v251, v251
	v_rcp_f32_e32 v3, v3
	s_nop 0
	v_mul_f32_e32 v3, v4, v3
	v_exp_f32_e64 v4, -v51
	s_nop 0
	v_fma_f32 v4, v4, v251, v251
	v_rcp_f32_e32 v4, v4
	s_nop 0
	v_mul_f32_e32 v4, v5, v4
	v_cvt_pk_bf16_f32 v3, v3, v4
	v_mad_i64_i32 v[4:5], s[6:7], v56, s57, v[120:121]
	v_lshl_add_u64 v[4:5], v[4:5], 0, v[122:123]
	global_store_dwordx4 v[4:5], v[0:3], off
	v_pk_mul_f32 v[4:5], v[34:35], v[6:7] op_sel_hi:[1,0]
	s_nop 0
	v_pk_mul_f32 v[0:1], v[36:37], v[6:7] op_sel_hi:[1,0]
	v_pk_mul_f32 v[2:3], v[38:39], v[6:7] op_sel_hi:[1,0]
	v_exp_f32_e64 v6, -v0
	v_mul_f32_e32 v0, v0, v28
	v_fma_f32 v6, v6, v251, v251
	v_rcp_f32_e32 v6, v6
	s_nop 0
	v_mul_f32_e32 v0, v0, v6
	v_exp_f32_e64 v6, -v1
	v_mul_f32_e32 v1, v1, v29
	v_fma_f32 v6, v6, v251, v251
	v_rcp_f32_e32 v6, v6
	s_nop 0
	v_mul_f32_e32 v1, v1, v6
	v_cvt_pk_bf16_f32 v0, v0, v1
	v_exp_f32_e64 v1, -v2
	v_mul_f32_e32 v2, v2, v30
	v_mul_f32_e32 v6, v33, v25
	v_fma_f32 v1, v1, v251, v251
	v_rcp_f32_e32 v1, v1
	s_nop 0
	v_mul_f32_e32 v1, v2, v1
	v_exp_f32_e64 v2, -v3
	v_mul_f32_e32 v3, v3, v31
	v_fma_f32 v2, v2, v251, v251
	v_rcp_f32_e32 v2, v2
	s_nop 0
	v_mul_f32_e32 v2, v3, v2
	v_cvt_pk_bf16_f32 v1, v1, v2
	v_exp_f32_e64 v2, -v32
	v_mul_f32_e32 v3, v32, v24
	v_add_u32_e32 v24, 48, v192
	v_fma_f32 v2, v2, v251, v251
	v_rcp_f32_e32 v2, v2
	s_nop 0
	v_mul_f32_e32 v2, v3, v2
	v_exp_f32_e64 v3, -v33
	s_nop 0
	v_fma_f32 v3, v3, v251, v251
	v_rcp_f32_e32 v3, v3
	s_nop 0
	v_mul_f32_e32 v3, v6, v3
	v_cvt_pk_bf16_f32 v2, v2, v3
	v_exp_f32_e64 v3, -v4
	v_mul_f32_e32 v4, v4, v26
	v_fma_f32 v3, v3, v251, v251
	v_rcp_f32_e32 v3, v3
	s_nop 0
	v_mul_f32_e32 v3, v4, v3
	v_exp_f32_e64 v4, -v5
	v_mul_f32_e32 v5, v5, v27
	v_fma_f32 v4, v4, v251, v251
	v_rcp_f32_e32 v4, v4
	s_nop 0
	v_mul_f32_e32 v4, v5, v4
	v_cvt_pk_bf16_f32 v3, v3, v4
	v_mad_i64_i32 v[4:5], s[6:7], v40, s57, v[120:121]
	v_lshl_add_u64 v[4:5], v[4:5], 0, v[122:123]
	global_store_dwordx4 v[4:5], v[0:3], off
	s_nop 1
	v_mov_b32_e32 v0, v7
	v_pk_mul_f32 v[4:5], v[20:21], v[0:1] op_sel_hi:[1,0]
	v_pk_mul_f32 v[2:3], v[22:23], v[0:1] op_sel_hi:[1,0]
	v_pk_mul_f32 v[6:7], v[18:19], v[0:1] op_sel_hi:[1,0]
	v_pk_mul_f32 v[16:17], v[16:17], v[0:1] op_sel_hi:[1,0]
	v_pk_mul_f32 v[14:15], v[14:15], v[0:1] op_sel_hi:[1,0]
	v_pk_mul_f32 v[12:13], v[12:13], v[0:1] op_sel_hi:[1,0]
	v_pk_mul_f32 v[10:11], v[10:11], v[0:1] op_sel_hi:[1,0]
	v_pk_mul_f32 v[8:9], v[8:9], v[0:1] op_sel_hi:[1,0]
	v_exp_f32_e64 v0, -v4
	v_mul_f32_e32 v1, v4, v12
	v_mul_f32_e32 v4, v5, v13
	v_fma_f32 v0, v0, v251, v251
	v_rcp_f32_e32 v0, v0
	s_nop 0
	v_mul_f32_e32 v0, v1, v0
	v_exp_f32_e64 v1, -v5
	v_mul_f32_e32 v5, v7, v11
	v_fma_f32 v1, v1, v251, v251
	v_rcp_f32_e32 v1, v1
	s_nop 0
	v_mul_f32_e32 v1, v4, v1
	v_cvt_pk_bf16_f32 v0, v0, v1
	v_exp_f32_e64 v1, -v2
	v_mul_f32_e32 v2, v2, v14
	v_mul_f32_e32 v4, v17, v9
	v_fma_f32 v1, v1, v251, v251
	v_rcp_f32_e32 v1, v1
	s_nop 0
	v_mul_f32_e32 v1, v2, v1
	v_exp_f32_e64 v2, -v3
	v_mul_f32_e32 v3, v3, v15
	v_fma_f32 v2, v2, v251, v251
	v_rcp_f32_e32 v2, v2
	s_nop 0
	v_mul_f32_e32 v2, v3, v2
	v_cvt_pk_bf16_f32 v1, v1, v2
	v_exp_f32_e64 v2, -v16
	v_mul_f32_e32 v3, v16, v8
	v_fma_f32 v2, v2, v251, v251
	v_rcp_f32_e32 v2, v2
	s_nop 0
	v_mul_f32_e32 v2, v3, v2
	v_exp_f32_e64 v3, -v17
	s_nop 0
	v_fma_f32 v3, v3, v251, v251
	v_rcp_f32_e32 v3, v3
	s_nop 0
	v_mul_f32_e32 v3, v4, v3
	v_cvt_pk_bf16_f32 v2, v2, v3
	v_exp_f32_e64 v3, -v6
	v_mul_f32_e32 v4, v6, v10
	v_fma_f32 v3, v3, v251, v251
	v_rcp_f32_e32 v3, v3
	s_nop 0
	v_mul_f32_e32 v3, v4, v3
	v_exp_f32_e64 v4, -v7
	s_nop 0
	v_fma_f32 v4, v4, v251, v251
	v_rcp_f32_e32 v4, v4
	s_nop 0
	v_mul_f32_e32 v4, v5, v4
	v_cvt_pk_bf16_f32 v3, v3, v4
	v_mad_i64_i32 v[4:5], s[6:7], v24, s57, v[120:121]
	v_lshl_add_u64 v[4:5], v[4:5], 0, v[122:123]
	s_mov_b64 s[6:7], -1
	global_store_dwordx4 v[4:5], v[0:3], off
	s_cbranch_vccnz .LBB0_159
	s_andn2_b64 vcc, exec, s[14:15]
	s_cbranch_vccnz .LBB0_158
	s_barrier
	s_branch .LBB0_158

; __device__ __forceinline__ unsigned cvt_pk_bf16(float lo, float hi) { unsigned r; asm volatile("v_cvt_pk_bf16_f32 %0, %1, %2" : "=v"(r) : "v"(lo), "v"(hi)); return r; }
; __device__ __forceinline__ float silu_mul(float g, float u) { const float e = __builtin_amdgcn_exp2f(g * -1.4426950408889634f); return g * u * __builtin_amdgcn_rcpf(1.0f + e); }
;     __device__ __forceinline__ void operator()(const f32x4 (&acc)[2][2][4][2], const Unit& u, int wr, int wc, int fr, int fq, const PG8_LAS float* rc, bool cached) const {
;     ...
;             for (int i = 0; i < (HALFM ? 4 : 8); ++i) rsv[i] = rc[(i >> 2) * HALF + wr * 64 + (i & 3) * 16 + fr + z];
;         } else rows_rstd<false>(rsv, ssq, row0, fq);
; #pragma unroll
;         for (int ai = 0; ai < (HALFM ? 1 : 2); ++ai)
; #pragma unroll
;             for (int m = 0; m < 4; ++m) { const int row = row0 + ai * HALF + m * 16; const float rs = rsv[ai * 4 + m];
;                 const f32x4 g0 = acc[ai][0][m][0] * rs, g1 = acc[ai][0][m][1] * rs, u0 = acc[ai][1][m][0] * rs, u1 = acc[ai][1][m][1] * rs;
;                 u32x4 w; w.x = cvt_pk_bf16(silu_mul(g0[0], u0[0]), silu_mul(g0[1], u0[1])); w.y = cvt_pk_bf16(silu_mul(g0[2], u0[2]), silu_mul(g0[3], u0[3]));
;                 w.z = cvt_pk_bf16(silu_mul(g1[0], u1[0]), silu_mul(g1[1], u1[1])); w.w = cvt_pk_bf16(silu_mul(g1[2], u1[2]), silu_mul(g1[3], u1[3]));
;                 *(u32x4*)(H + (size_t)row * 5632 + col0) = w; }
.LBB0_198:
	v_lshl_or_b32 v4, s39, 7, v128
	s_waitcnt lgkmcnt(0)
	v_mul_f32_e32 v0, 0x3fb8aa3b, v0
	v_mul_f32_e32 v1, 0x3fb8aa3b, v1
	v_mul_f32_e32 v2, 0x3fb8aa3b, v2
	v_mul_f32_e32 v3, 0x3fb8aa3b, v3
	v_mov_b32_e32 v251, 0x40053526
	v_pk_mul_f32 v[68:69], v[68:69], v[0:1] op_sel_hi:[1,0]
	v_add_u32_e32 v6, v4, v130
	v_pk_mul_f32 v[4:5], v[70:71], v[0:1] op_sel_hi:[1,0]
	v_pk_mul_f32 v[70:71], v[58:59], v[0:1] op_sel_hi:[1,0]
	v_pk_mul_f32 v[58:59], v[56:57], v[0:1] op_sel_hi:[1,0]
	v_exp_f32_e64 v56, -v68
	v_pk_mul_f32 v[60:61], v[60:61], v[0:1] op_sel_hi:[1,0]
	v_pk_mul_f32 v[62:63], v[62:63], v[0:1] op_sel_hi:[1,0]
	v_mul_f32_e32 v57, v68, v60
	v_fma_f32 v56, v56, v251, v251
	v_rcp_f32_e32 v56, v56
	v_mul_f32_e32 v60, v69, v61
	v_pk_mul_f32 v[64:65], v[64:65], v[0:1] op_sel_hi:[1,0]
	v_pk_mul_f32 v[66:67], v[66:67], v[0:1] op_sel_hi:[1,0]
	v_mul_f32_e32 v56, v57, v56
	v_exp_f32_e64 v57, -v69
	v_ashrrev_i32_e32 v7, 31, v6
	v_lshlrev_b64 v[6:7], 1, v[6:7]
	v_pk_mul_f32 v[52:53], v[52:53], v[0:1] op_sel:[0,1]
	v_fma_f32 v57, v57, v251, v251
	v_rcp_f32_e32 v57, v57
	v_pk_mul_f32 v[54:55], v[54:55], v[0:1] op_sel:[0,1]
	v_pk_mul_f32 v[50:51], v[50:51], v[0:1] op_sel:[0,1]
	v_pk_mul_f32 v[48:49], v[48:49], v[0:1] op_sel:[0,1]
	v_mul_f32_e32 v57, v60, v57
	v_cvt_pk_bf16_f32 v56, v56, v57
	v_exp_f32_e64 v57, -v4
	v_mul_f32_e32 v4, v4, v62
	v_pk_mul_f32 v[46:47], v[46:47], v[0:1] op_sel:[0,1]
	v_pk_mul_f32 v[44:45], v[44:45], v[0:1] op_sel:[0,1]
	v_fma_f32 v57, v57, v251, v251
	v_rcp_f32_e32 v57, v57
	v_pk_mul_f32 v[36:37], v[36:37], v[2:3] op_sel_hi:[1,0]
	v_pk_mul_f32 v[34:35], v[34:35], v[2:3] op_sel_hi:[1,0]
	v_pk_mul_f32 v[32:33], v[32:33], v[2:3] op_sel_hi:[1,0]
	v_mul_f32_e32 v4, v4, v57
	v_exp_f32_e64 v57, -v5
	v_mul_f32_e32 v5, v5, v63
	v_pk_mul_f32 v[30:31], v[30:31], v[2:3] op_sel_hi:[1,0]
	v_pk_mul_f32 v[28:29], v[28:29], v[2:3] op_sel_hi:[1,0]
	v_fma_f32 v57, v57, v251, v251
	v_rcp_f32_e32 v57, v57
	s_andn2_b64 vcc, exec, s[4:5]
	v_mul_f32_e32 v5, v5, v57
	v_cvt_pk_bf16_f32 v57, v4, v5
	v_exp_f32_e64 v4, -v64
	v_mul_f32_e32 v5, v64, v58
	v_mul_f32_e32 v58, v65, v59
	v_mul_f32_e32 v59, v67, v71
	v_fma_f32 v4, v4, v251, v251
	v_rcp_f32_e32 v4, v4
	s_nop 0
	v_mul_f32_e32 v4, v5, v4
	v_exp_f32_e64 v5, -v65
	s_nop 0
	v_fma_f32 v5, v5, v251, v251
	v_rcp_f32_e32 v5, v5
	s_nop 0
	v_mul_f32_e32 v5, v58, v5
	v_cvt_pk_bf16_f32 v58, v4, v5
	v_exp_f32_e64 v4, -v66
	v_mul_f32_e32 v5, v66, v70
	v_fma_f32 v4, v4, v251, v251
	v_rcp_f32_e32 v4, v4
	s_nop 0
	v_mul_f32_e32 v4, v5, v4
	v_exp_f32_e64 v5, -v67
	s_nop 0
	v_fma_f32 v5, v5, v251, v251
	v_rcp_f32_e32 v5, v5
	s_nop 0
	v_mul_f32_e32 v5, v59, v5
	v_cvt_pk_bf16_f32 v59, v4, v5
	v_mov_b64_e32 v[4:5], s[20:21]
	v_mad_u64_u32 v[60:61], s[6:7], v122, s57, v[4:5]
	v_mov_b32_e32 v62, v61
	v_mad_u64_u32 v[62:63], s[6:7], v123, s57, v[62:63]
	v_mov_b32_e32 v61, v62
	v_lshl_add_u64 v[60:61], v[60:61], 0, v[6:7]
	global_store_dwordx4 v[60:61], v[56:59], off
	s_nop 1
	v_pk_mul_f32 v[56:57], v[42:43], v[0:1] op_sel:[0,1]
	v_pk_mul_f32 v[0:1], v[40:41], v[0:1] op_sel:[0,1]
	v_exp_f32_e64 v40, -v52
	v_mul_f32_e32 v41, v52, v44
	v_mul_f32_e32 v42, v53, v45
	v_mul_f32_e32 v43, v55, v47
	v_fma_f32 v40, v40, v251, v251
	v_rcp_f32_e32 v40, v40
	v_mul_f32_e32 v0, v48, v0
	v_mul_f32_e32 v1, v49, v1
	v_mul_f32_e32 v40, v41, v40
	v_exp_f32_e64 v41, -v53
	s_nop 0
	v_fma_f32 v41, v41, v251, v251
	v_rcp_f32_e32 v41, v41
	s_nop 0
	v_mul_f32_e32 v41, v42, v41
	v_cvt_pk_bf16_f32 v40, v40, v41
	v_exp_f32_e64 v41, -v54
	v_mul_f32_e32 v42, v54, v46
	v_fma_f32 v41, v41, v251, v251
	v_rcp_f32_e32 v41, v41
	s_nop 0
	v_mul_f32_e32 v41, v42, v41
	v_exp_f32_e64 v42, -v55
	s_nop 0
	v_fma_f32 v42, v42, v251, v251
	v_rcp_f32_e32 v42, v42
	s_nop 0
	v_mul_f32_e32 v42, v43, v42
	v_cvt_pk_bf16_f32 v41, v41, v42
	v_exp_f32_e64 v42, -v48
	v_mul_f32_e32 v43, v51, v57
	v_fma_f32 v42, v42, v251, v251
	v_rcp_f32_e32 v42, v42
	s_nop 0
	v_mul_f32_e32 v0, v0, v42
	v_exp_f32_e64 v42, -v49
	s_nop 0
	v_fma_f32 v42, v42, v251, v251
	v_rcp_f32_e32 v42, v42
	s_nop 0
	v_mul_f32_e32 v1, v1, v42
	v_cvt_pk_bf16_f32 v42, v0, v1
	v_exp_f32_e64 v0, -v50
	v_mul_f32_e32 v1, v50, v56
	v_fma_f32 v0, v0, v251, v251
	v_rcp_f32_e32 v0, v0
; __device__ __forceinline__ unsigned cvt_pk_bf16(float lo, float hi) { unsigned r; asm volatile("v_cvt_pk_bf16_f32 %0, %1, %2" : "=v"(r) : "v"(lo), "v"(hi)); return r; }
; __device__ __forceinline__ float silu_mul(float g, float u) { const float e = __builtin_amdgcn_exp2f(g * -1.4426950408889634f); return g * u * __builtin_amdgcn_rcpf(1.0f + e); }
;     __device__ __forceinline__ void operator()(const f32x4 (&acc)[2][2][4][2], const Unit& u, int wr, int wc, int fr, int fq, const PG8_LAS float* rc, bool cached) const {
;     ...
;             for (int m = 0; m < 4; ++m) { const int row = row0 + ai * HALF + m * 16; const float rs = rsv[ai * 4 + m];
;                 const f32x4 g0 = acc[ai][0][m][0] * rs, g1 = acc[ai][0][m][1] * rs, u0 = acc[ai][1][m][0] * rs, u1 = acc[ai][1][m][1] * rs;
;                 u32x4 w; w.x = cvt_pk_bf16(silu_mul(g0[0], u0[0]), silu_mul(g0[1], u0[1])); w.y = cvt_pk_bf16(silu_mul(g0[2], u0[2]), silu_mul(g0[3], u0[3]));
;                 w.z = cvt_pk_bf16(silu_mul(g1[0], u1[0]), silu_mul(g1[1], u1[1])); w.w = cvt_pk_bf16(silu_mul(g1[2], u1[2]), silu_mul(g1[3], u1[3]));
;                 *(u32x4*)(H + (size_t)row * 5632 + col0) = w; }
	s_nop 0
	v_mul_f32_e32 v0, v1, v0
	v_exp_f32_e64 v1, -v51
	s_nop 0
	v_fma_f32 v1, v1, v251, v251
	v_rcp_f32_e32 v1, v1
	s_nop 0
	v_mul_f32_e32 v1, v43, v1
	v_cvt_pk_bf16_f32 v43, v0, v1
	v_mad_u64_u32 v[0:1], s[6:7], v120, s57, v[4:5]
	v_mov_b32_e32 v44, v1
	v_mad_u64_u32 v[44:45], s[6:7], v121, s57, v[44:45]
	v_mov_b32_e32 v1, v44
	v_lshl_add_u64 v[0:1], v[0:1], 0, v[6:7]
	global_store_dwordx4 v[0:1], v[40:43], off
	v_pk_mul_f32 v[0:1], v[38:39], v[2:3] op_sel_hi:[1,0]
	v_pk_mul_f32 v[38:39], v[26:27], v[2:3] op_sel_hi:[1,0]
	v_pk_mul_f32 v[26:27], v[24:25], v[2:3] op_sel_hi:[1,0]
	v_exp_f32_e64 v2, -v36
	v_mul_f32_e32 v24, v36, v28
	v_mul_f32_e32 v25, v37, v29
	v_fma_f32 v2, v2, v251, v251
	v_rcp_f32_e32 v2, v2
	s_nop 0
	v_mul_f32_e32 v2, v24, v2
	v_exp_f32_e64 v24, -v37
	s_nop 0
	v_fma_f32 v24, v24, v251, v251
	v_rcp_f32_e32 v24, v24
	s_nop 0
	v_mul_f32_e32 v24, v25, v24
	v_cvt_pk_bf16_f32 v24, v2, v24
	v_exp_f32_e64 v2, -v0
	v_mul_f32_e32 v0, v0, v30
	v_fma_f32 v2, v2, v251, v251
	v_rcp_f32_e32 v2, v2
	s_nop 0
	v_mul_f32_e32 v0, v0, v2
	v_exp_f32_e64 v2, -v1
	v_mul_f32_e32 v1, v1, v31
	v_fma_f32 v2, v2, v251, v251
	v_rcp_f32_e32 v2, v2
	s_nop 0
	v_mul_f32_e32 v1, v1, v2
	v_cvt_pk_bf16_f32 v25, v0, v1
	v_exp_f32_e64 v0, -v32
	v_mul_f32_e32 v1, v32, v26
	v_mul_f32_e32 v2, v33, v27
	v_fma_f32 v0, v0, v251, v251
	v_rcp_f32_e32 v0, v0
	s_nop 0
	v_mul_f32_e32 v0, v1, v0
	v_exp_f32_e64 v1, -v33
	s_nop 0
	v_fma_f32 v1, v1, v251, v251
	v_rcp_f32_e32 v1, v1
	s_nop 0
	v_mul_f32_e32 v1, v2, v1
	v_cvt_pk_bf16_f32 v26, v0, v1
	v_exp_f32_e64 v0, -v34
	v_mul_f32_e32 v1, v34, v38
	v_mul_f32_e32 v2, v35, v39
	v_fma_f32 v0, v0, v251, v251
	v_rcp_f32_e32 v0, v0
	s_nop 0
	v_mul_f32_e32 v0, v1, v0
	v_exp_f32_e64 v1, -v35
	s_nop 0
	v_fma_f32 v1, v1, v251, v251
	v_rcp_f32_e32 v1, v1
	s_nop 0
	v_mul_f32_e32 v1, v2, v1
	v_cvt_pk_bf16_f32 v27, v0, v1
	v_mad_u64_u32 v[0:1], s[6:7], v118, s57, v[4:5]
	v_mov_b32_e32 v2, v1
	v_mad_u64_u32 v[28:29], s[6:7], v119, s57, v[2:3]
	v_mov_b32_e32 v1, v28
	v_lshl_add_u64 v[0:1], v[0:1], 0, v[6:7]
	global_store_dwordx4 v[0:1], v[24:27], off
	v_mov_b32_e32 v0, v3
	v_pk_mul_f32 v[20:21], v[20:21], v[0:1] op_sel_hi:[1,0]
	v_pk_mul_f32 v[2:3], v[22:23], v[0:1] op_sel_hi:[1,0]
	v_pk_mul_f32 v[18:19], v[18:19], v[0:1] op_sel_hi:[1,0]
	v_pk_mul_f32 v[16:17], v[16:17], v[0:1] op_sel_hi:[1,0]
	v_pk_mul_f32 v[14:15], v[14:15], v[0:1] op_sel_hi:[1,0]
	v_pk_mul_f32 v[12:13], v[12:13], v[0:1] op_sel_hi:[1,0]
	v_pk_mul_f32 v[10:11], v[10:11], v[0:1] op_sel_hi:[1,0]
	v_pk_mul_f32 v[8:9], v[8:9], v[0:1] op_sel_hi:[1,0]
	v_exp_f32_e64 v0, -v20
	v_mul_f32_e32 v1, v20, v12
	v_mul_f32_e32 v12, v21, v13
	v_mad_u64_u32 v[4:5], s[6:7], v116, s57, v[4:5]
	v_fma_f32 v0, v0, v251, v251
	v_rcp_f32_e32 v0, v0
	s_nop 0
	v_mul_f32_e32 v0, v1, v0
	v_exp_f32_e64 v1, -v21
	s_nop 0
	v_fma_f32 v1, v1, v251, v251
	v_rcp_f32_e32 v1, v1
	s_nop 0
	v_mul_f32_e32 v1, v12, v1
	v_cvt_pk_bf16_f32 v0, v0, v1
	v_exp_f32_e64 v1, -v2
	v_mul_f32_e32 v2, v2, v14
	v_fma_f32 v1, v1, v251, v251
	v_rcp_f32_e32 v1, v1
	s_nop 0
	v_mul_f32_e32 v1, v2, v1
	v_exp_f32_e64 v2, -v3
	v_mul_f32_e32 v3, v3, v15
	v_fma_f32 v2, v2, v251, v251
	v_rcp_f32_e32 v2, v2
	s_nop 0
	v_mul_f32_e32 v2, v3, v2
	v_cvt_pk_bf16_f32 v1, v1, v2
	v_exp_f32_e64 v2, -v16
	v_mul_f32_e32 v3, v16, v8
	v_mul_f32_e32 v8, v17, v9
	v_mul_f32_e32 v9, v19, v11
	v_fma_f32 v2, v2, v251, v251
	v_rcp_f32_e32 v2, v2
	s_nop 0
	v_mul_f32_e32 v2, v3, v2
	v_exp_f32_e64 v3, -v17
	s_nop 0
	v_fma_f32 v3, v3, v251, v251
	v_rcp_f32_e32 v3, v3
	s_nop 0
	v_mul_f32_e32 v3, v8, v3
	v_cvt_pk_bf16_f32 v2, v2, v3
	v_exp_f32_e64 v3, -v18
	v_mul_f32_e32 v8, v18, v10
	v_fma_f32 v3, v3, v251, v251
	v_rcp_f32_e32 v3, v3
	s_nop 0
	v_mul_f32_e32 v3, v8, v3
	v_exp_f32_e64 v8, -v19
	s_nop 0
	v_fma_f32 v8, v8, v251, v251
	v_rcp_f32_e32 v8, v8
	s_nop 0
	v_mul_f32_e32 v8, v9, v8
	v_cvt_pk_bf16_f32 v3, v3, v8
	v_mov_b32_e32 v8, v5
	v_mad_u64_u32 v[8:9], s[6:7], v117, s57, v[8:9]
	v_mov_b32_e32 v5, v8
	v_lshl_add_u64 v[4:5], v[4:5], 0, v[6:7]
	s_mov_b64 s[6:7], -1
	global_store_dwordx4 v[4:5], v[0:3], off
	s_cbranch_vccnz .LBB0_184
	s_andn2_b64 vcc, exec, s[16:17]
	s_cbranch_vccnz .LBB0_183
	s_barrier
	s_branch .LBB0_183
